# c3 QK^T block: ds_read_b128 operand pairs software-pipelined 4 deep with counted lgkmcnt (was lgkmcnt(0) per MFMA)
# speedup vs baseline: 1.0075x; 1.0075x over previous
; __device__ __forceinline__ unsigned pk2(float lo, float hi) { unsigned r; asm volatile("v_cvt_pk_bf16_f32 %0, %1, %2" : "=v"(r) : "v"(lo), "v"(hi)); return r; }
; __device__ __forceinline__ void unpack8(const u32x4 w, float* o) { o[0] = bflo(w.x); o[1] = bfhi(w.x); o[2] = bflo(w.y); o[3] = bfhi(w.y); o[4] = bflo(w.z); o[5] = bfhi(w.z); o[6] = bflo(w.w); o[7] = bfhi(w.w); }
; __device__ __forceinline__ void gla_c3(const Args& a, int l, unsigned char* sm, const bf16_t* __restrict__ PC, const bf16_t* __restrict__ PLR, const bf16_t* __restrict__ UPD, bf16_t* __restrict__ OC) {
;     ...
;             {
;                 const int j = tid >> 3, d0 = (tid & 7) * 16;
;                 float qv[16], kv[16];
;                 unpack8(qraw[0], qv); unpack8(qraw[1], qv + 8);
;                 unpack8(kraw[0], kv); unpack8(kraw[1], kv + 8);
;                 float qo[16], ko[16];
; #pragma unroll
;                 for (int e = 0; e < 16; ++e) { const float b = Gb[j * 129 + d0 + e]; qo[e] = qv[e] * 0.08838834764831845f * __expf(b); ko[e] = kv[e] * __expf(-b); }
;                 u32x4 w;
;                 w.x = pk2(qo[0], qo[1]); w.y = pk2(qo[2], qo[3]); w.z = pk2(qo[4], qo[5]); w.w = pk2(qo[6], qo[7]); *(u32x4*)(qeL + j * 136 + d0) = w;
;                 w.x = pk2(qo[8], qo[9]); w.y = pk2(qo[10], qo[11]); w.z = pk2(qo[12], qo[13]); w.w = pk2(qo[14], qo[15]); *(u32x4*)(qeL + j * 136 + d0 + 8) = w;
;                 w.x = pk2(ko[0], ko[1]); w.y = pk2(ko[2], ko[3]); w.z = pk2(ko[4], ko[5]); w.w = pk2(ko[6], ko[7]); *(u32x4*)(keL + j * 136 + d0) = w;
;                 w.x = pk2(ko[8], ko[9]); w.y = pk2(ko[10], ko[11]); w.z = pk2(ko[12], ko[13]); w.w = pk2(ko[14], ko[15]); *(u32x4*)(keL + j * 136 + d0 + 8) = w;
;             }
;             __syncthreads();
;             if (wid < 4) {
.LBB0_478:
	s_or_b64 exec, exec, s[4:5]
	s_waitcnt lgkmcnt(0)
	s_barrier
	ds_read2_b32 v[32:33], v103 offset1:1
	ds_read2_b32 v[36:37], v103 offset0:2 offset1:3
	ds_read2_b32 v[40:41], v103 offset0:4 offset1:5
	ds_read2_b32 v[44:45], v103 offset0:6 offset1:7
	s_xor_b64 s[4:5], s[28:29], -1
	s_waitcnt lgkmcnt(3)
	v_mul_f32_e32 v34, 0x3fb8aa3b, v32
	v_mul_f32_e32 v32, 0xbfb8aa3b, v32
	v_mul_f32_e32 v35, 0x3fb8aa3b, v33
	s_waitcnt lgkmcnt(0)
	v_mul_f32_e32 v46, 0x3fb8aa3b, v44
	v_mul_f32_e32 v44, 0xbfb8aa3b, v44
	v_exp_f32_e32 v44, v44
	v_exp_f32_e32 v46, v46
	v_mul_f32_e32 v33, 0xbfb8aa3b, v33
	v_mul_f32_e32 v38, 0x3fb8aa3b, v36
	v_mul_f32_e32 v64, v44, v114
	v_mul_f32_e32 v44, 0x3fb8aa3b, v45
	v_exp_f32_e32 v44, v44
	v_mul_f32_e32 v47, v130, v46
	v_mul_f32_e32 v39, 0x3fb8aa3b, v37
	v_mul_f32_e32 v42, 0x3fb8aa3b, v40
	v_mul_f32_e32 v140, v131, v44
	v_mul_f32_e32 v44, 0xbfb8aa3b, v45
	v_exp_f32_e32 v44, v44
	v_mul_f32_e32 v43, 0x3fb8aa3b, v41
	v_exp_f32_e32 v34, v34
	v_exp_f32_e32 v32, v32
	v_mul_f32_e32 v141, v44, v115
	ds_read2_b32 v[44:45], v103 offset0:8 offset1:9
	v_exp_f32_e32 v35, v35
	v_exp_f32_e32 v33, v33
	v_exp_f32_e32 v38, v38
	v_mul_f32_e32 v36, 0xbfb8aa3b, v36
	s_waitcnt lgkmcnt(0)
	v_mul_f32_e32 v46, 0x3fb8aa3b, v44
	v_mul_f32_e32 v44, 0xbfb8aa3b, v44
	v_exp_f32_e32 v44, v44
	v_exp_f32_e32 v46, v46
	v_exp_f32_e32 v39, v39
	v_mul_f32_e32 v37, 0xbfb8aa3b, v37
	v_mul_f32_e32 v143, v44, v116
	v_mul_f32_e32 v44, 0x3fb8aa3b, v45
	v_exp_f32_e32 v44, v44
	v_mul_f32_e32 v142, v132, v46
	v_exp_f32_e32 v42, v42
	v_mul_f32_e32 v40, 0xbfb8aa3b, v40
	v_mul_f32_e32 v144, v133, v44
	v_mul_f32_e32 v44, 0xbfb8aa3b, v45
	v_exp_f32_e32 v44, v44
	v_exp_f32_e32 v43, v43
	v_mul_f32_e32 v41, 0xbfb8aa3b, v41
	v_exp_f32_e32 v36, v36
	v_mul_f32_e32 v145, v44, v117
	ds_read2_b32 v[44:45], v103 offset0:10 offset1:11
	v_exp_f32_e32 v37, v37
	v_exp_f32_e32 v40, v40
	v_exp_f32_e32 v41, v41
	v_mul_f32_e32 v34, v124, v34
	s_waitcnt lgkmcnt(0)
	v_mul_f32_e32 v46, 0x3fb8aa3b, v44
	v_mul_f32_e32 v44, 0xbfb8aa3b, v44
	v_exp_f32_e32 v44, v44
	v_exp_f32_e32 v46, v46
	v_mul_f32_e32 v32, v32, v91
	v_mul_f32_e32 v35, v125, v35
	v_mul_f32_e32 v147, v44, v118
	v_mul_f32_e32 v44, 0x3fb8aa3b, v45
	v_exp_f32_e32 v44, v44
	v_mul_f32_e32 v146, v134, v46
	v_mul_f32_e32 v33, v33, v93
	v_mul_f32_e32 v38, v126, v38
	v_mul_f32_e32 v148, v135, v44
	v_mul_f32_e32 v44, 0xbfb8aa3b, v45
	v_exp_f32_e32 v44, v44
	v_mul_f32_e32 v39, v127, v39
	v_mul_f32_e32 v42, v128, v42
	v_mul_f32_e32 v43, v129, v43
	v_mul_f32_e32 v149, v44, v119
	ds_read2_b32 v[44:45], v103 offset0:12 offset1:13
	v_mul_f32_e32 v36, v36, v110
	v_mul_f32_e32 v37, v37, v111
	v_mul_f32_e32 v40, v40, v112
	v_mul_f32_e32 v41, v41, v113
	s_waitcnt lgkmcnt(0)
	v_mul_f32_e32 v46, 0x3fb8aa3b, v44
	v_mul_f32_e32 v44, 0xbfb8aa3b, v44
	v_exp_f32_e32 v44, v44
	v_exp_f32_e32 v46, v46
	v_mul_f32_e32 v151, v44, v120
	v_mul_f32_e32 v44, 0x3fb8aa3b, v45
	v_exp_f32_e32 v44, v44
	v_mul_f32_e32 v150, v136, v46
	v_mul_f32_e32 v152, v137, v44
	v_mul_f32_e32 v44, 0xbfb8aa3b, v45
	v_exp_f32_e32 v44, v44
	s_nop 0
	v_mul_f32_e32 v153, v44, v121
	ds_read2_b32 v[44:45], v103 offset0:14 offset1:15
	s_waitcnt lgkmcnt(0)
	v_mul_f32_e32 v46, 0x3fb8aa3b, v44
	v_mul_f32_e32 v44, 0xbfb8aa3b, v44
	v_exp_f32_e32 v44, v44
	v_exp_f32_e32 v46, v46
	v_mul_f32_e32 v155, v44, v122
	v_mul_f32_e32 v44, 0x3fb8aa3b, v45
	v_exp_f32_e32 v44, v44
	v_mul_f32_e32 v154, v138, v46
	v_mul_f32_e32 v156, v139, v44
	v_mul_f32_e32 v44, 0xbfb8aa3b, v45
	v_exp_f32_e32 v44, v44
	s_nop 0
	v_mul_f32_e32 v157, v44, v123
	v_cvt_pk_bf16_f32 v44, v34, v35
	v_cvt_pk_bf16_f32 v45, v38, v39
	v_cvt_pk_bf16_f32 v46, v42, v43
	v_cvt_pk_bf16_f32 v47, v47, v140
	ds_write_b128 v84, v[44:47] offset:47872
	v_cvt_pk_bf16_f32 v42, v142, v144
	v_cvt_pk_bf16_f32 v43, v146, v148
	v_cvt_pk_bf16_f32 v44, v150, v152
	v_cvt_pk_bf16_f32 v45, v154, v156
	ds_write_b128 v84, v[42:45] offset:47888
	v_cvt_pk_bf16_f32 v32, v32, v33
	v_cvt_pk_bf16_f32 v33, v36, v37
	v_cvt_pk_bf16_f32 v34, v40, v41
	v_cvt_pk_bf16_f32 v35, v64, v141
	ds_write_b128 v84, v[32:35] offset:65280
	v_cvt_pk_bf16_f32 v32, v143, v145
	v_cvt_pk_bf16_f32 v33, v147, v149
	v_cvt_pk_bf16_f32 v34, v151, v153
	v_cvt_pk_bf16_f32 v35, v155, v157
	ds_write_b128 v84, v[32:35] offset:65296
	s_waitcnt lgkmcnt(0)
	s_barrier
	s_and_saveexec_b64 s[34:35], s[38:39]
	s_cbranch_execz .LBB0_455
; __device__ __forceinline__ bf16_t f2bf(float f) { return (bf16_t)(pk2(f, 0.f) & 0xffffu); }
; __device__ __forceinline__ void gla_c3(const Args& a, int l, unsigned char* sm, const bf16_t* __restrict__ PC, const bf16_t* __restrict__ PLR, const bf16_t* __restrict__ UPD, bf16_t* __restrict__ OC) {
;     ...
;                 f32x16 s;
; #pragma unroll
;                 for (int e = 0; e < 16; ++e) s[e] = 0.f;
; #pragma unroll
;                 for (int ks = 0; ks < 8; ++ks) {
;                     const bf16x8 av = *(const bf16x8*)(qeL + (32 * mi + r) * 136 + ks * 16 + 8 * h);
;                     const bf16x8 bv = *(const bf16x8*)(keL + (32 * ni + r) * 136 + ks * 16 + 8 * h);
;                     s = __builtin_amdgcn_mfma_f32_32x32x16_bf16(av, bv, s, 0, 0, 0);
;                 }
; #pragma unroll
;                 for (int e = 0; e < 16; ++e) { const int i = 32 * mi + (e & 3) + 8 * (e >> 2) + 4 * h, j = 32 * ni + r; const bool keep = dir ? (j >= i) : (j <= i); Aa[i * 72 + j] = f2bf(keep ? s[e] : 0.f); }
	ds_read_b128 v[204:207], v86 offset:47872
	ds_read_b128 v[220:223], v85 offset:65280
	ds_read_b128 v[208:211], v86 offset:47904
	ds_read_b128 v[224:227], v85 offset:65312
	ds_read_b128 v[212:215], v86 offset:47936
	ds_read_b128 v[228:231], v85 offset:65344
	ds_read_b128 v[216:219], v86 offset:47968
	ds_read_b128 v[232:235], v85 offset:65376
	v_readlane_b32 s2, v245, 48
	v_readlane_b32 s3, v245, 49
	s_waitcnt lgkmcnt(6)
	v_mfma_f32_32x32x16_bf16 v[32:47], v[204:207], v[220:223], 0
	ds_read_b128 v[204:207], v86 offset:48000
	ds_read_b128 v[220:223], v85 offset:65408
	v_cndmask_b32_e64 v64, 0, 1, s[2:3]
	v_readlane_b32 s2, v245, 46
	v_readlane_b32 s3, v245, 47
	s_waitcnt lgkmcnt(6)
	v_mfma_f32_32x32x16_bf16 v[32:47], v[208:211], v[224:227], v[32:47]
	ds_read_b128 v[208:211], v86 offset:48032
	ds_read_b128 v[224:227], v85 offset:65440
	s_waitcnt lgkmcnt(6)
	v_mfma_f32_32x32x16_bf16 v[32:47], v[212:215], v[228:231], v[32:47]
	ds_read_b128 v[212:215], v86 offset:48064
	ds_read_b128 v[228:231], v85 offset:65472
	s_waitcnt lgkmcnt(6)
	v_mfma_f32_32x32x16_bf16 v[32:47], v[216:219], v[232:235], v[32:47]
	ds_read_b128 v[216:219], v86 offset:48096
	ds_read_b128 v[232:235], v85 offset:65504
	s_waitcnt lgkmcnt(6)
	v_mfma_f32_32x32x16_bf16 v[32:47], v[204:207], v[220:223], v[32:47]
	s_waitcnt lgkmcnt(4)
	v_mfma_f32_32x32x16_bf16 v[32:47], v[208:211], v[224:227], v[32:47]
	s_waitcnt lgkmcnt(2)
	v_mfma_f32_32x32x16_bf16 v[32:47], v[212:215], v[228:231], v[32:47]
	s_waitcnt lgkmcnt(0)
	v_mfma_f32_32x32x16_bf16 v[32:47], v[216:219], v[232:235], v[32:47]
	v_cndmask_b32_e64 v140, 0, 1, s[2:3]
	v_cndmask_b32_e64 v64, v140, v64, s[28:29]
	v_and_b32_e32 v64, 1, v64
	v_cmp_eq_u32_e32 vcc, 1, v64
	v_readlane_b32 s2, v245, 52
	v_readlane_b32 s3, v245, 53
	s_nop 5
	v_cndmask_b32_e32 v32, 0, v32, vcc
	v_cvt_pk_bf16_f32 v32, v32, v65
	ds_write_b16 v104, v32
	v_cndmask_b32_e64 v32, 0, 1, s[2:3]
	v_readlane_b32 s2, v245, 50
	v_readlane_b32 s3, v245, 51
	s_nop 1
	v_cndmask_b32_e64 v64, 0, 1, s[2:3]
	v_cndmask_b32_e64 v32, v64, v32, s[28:29]
	v_and_b32_e32 v32, 1, v32
	v_cmp_eq_u32_e32 vcc, 1, v32
	v_readlane_b32 s2, v245, 56
	v_readlane_b32 s3, v245, 57
	v_cndmask_b32_e32 v32, 0, v33, vcc
	v_cvt_pk_bf16_f32 v32, v32, v65
	ds_write_b16 v104, v32 offset:144
	v_cndmask_b32_e64 v32, 0, 1, s[2:3]
	v_readlane_b32 s2, v245, 54
	v_readlane_b32 s3, v245, 55
	s_nop 1
	v_cndmask_b32_e64 v33, 0, 1, s[2:3]
	v_cndmask_b32_e64 v32, v33, v32, s[28:29]
	v_and_b32_e32 v32, 1, v32
	v_cmp_eq_u32_e32 vcc, 1, v32
	v_readlane_b32 s2, v245, 60
	v_readlane_b32 s3, v245, 61
	v_cndmask_b32_e32 v32, 0, v34, vcc
	v_cvt_pk_bf16_f32 v32, v32, v65
	ds_write_b16 v104, v32 offset:288
	v_cndmask_b32_e64 v32, 0, 1, s[2:3]
	v_readlane_b32 s2, v245, 58
	v_readlane_b32 s3, v245, 59
	s_nop 1
	v_cndmask_b32_e64 v33, 0, 1, s[2:3]
	v_cndmask_b32_e64 v32, v33, v32, s[28:29]
	v_and_b32_e32 v32, 1, v32
	v_cmp_eq_u32_e32 vcc, 1, v32
	v_readlane_b32 s2, v244, 0
	v_readlane_b32 s3, v244, 1
	v_cndmask_b32_e32 v32, 0, v35, vcc
	v_cvt_pk_bf16_f32 v32, v32, v65
	ds_write_b16 v104, v32 offset:432
	v_cndmask_b32_e64 v32, 0, 1, s[2:3]
	v_readlane_b32 s2, v245, 62
	v_readlane_b32 s3, v245, 63
	s_nop 1
	v_cndmask_b32_e64 v33, 0, 1, s[2:3]
	v_cndmask_b32_e64 v32, v33, v32, s[28:29]
	v_and_b32_e32 v32, 1, v32
	v_cmp_eq_u32_e32 vcc, 1, v32
	v_readlane_b32 s2, v244, 4
	v_readlane_b32 s3, v244, 5
	v_cndmask_b32_e32 v32, 0, v36, vcc
	v_cvt_pk_bf16_f32 v32, v32, v65
	ds_write_b16 v104, v32 offset:1152
	v_cndmask_b32_e64 v32, 0, 1, s[2:3]
	v_readlane_b32 s2, v244, 2
	v_readlane_b32 s3, v244, 3
	s_nop 1
	v_cndmask_b32_e64 v33, 0, 1, s[2:3]
	v_cndmask_b32_e64 v32, v33, v32, s[28:29]
	v_and_b32_e32 v32, 1, v32
	v_cmp_eq_u32_e32 vcc, 1, v32
	v_cndmask_b32_e64 v33, 0, 1, s[48:49]
	s_nop 0
	v_cndmask_b32_e32 v32, 0, v37, vcc
	v_cvt_pk_bf16_f32 v32, v32, v65
	ds_write_b16 v104, v32 offset:1296
	v_cndmask_b32_e64 v32, 0, 1, s[50:51]
	v_cndmask_b32_e64 v32, v33, v32, s[28:29]
	v_and_b32_e32 v32, 1, v32
	v_cmp_eq_u32_e32 vcc, 1, v32
	v_cndmask_b32_e64 v33, 0, 1, s[52:53]
	s_nop 0
	v_cndmask_b32_e32 v32, 0, v38, vcc
	v_cvt_pk_bf16_f32 v32, v32, v65
	ds_write_b16 v104, v32 offset:1440
	v_cndmask_b32_e64 v32, 0, 1, s[54:55]
	v_cndmask_b32_e64 v32, v33, v32, s[28:29]
	v_and_b32_e32 v32, 1, v32
	v_cmp_eq_u32_e32 vcc, 1, v32
	v_cndmask_b32_e64 v33, 0, 1, s[56:57]
	s_nop 0
	v_cndmask_b32_e32 v32, 0, v39, vcc
	v_cvt_pk_bf16_f32 v32, v32, v65
	ds_write_b16 v104, v32 offset:1584
	v_cndmask_b32_e64 v32, 0, 1, s[58:59]
	v_cndmask_b32_e64 v32, v33, v32, s[28:29]
	v_and_b32_e32 v32, 1, v32
	v_cmp_eq_u32_e32 vcc, 1, v32
	v_cndmask_b32_e64 v33, 0, 1, s[40:41]
	s_nop 0
	v_cndmask_b32_e32 v32, 0, v40, vcc
	v_cvt_pk_bf16_f32 v32, v32, v65
	ds_write_b16 v104, v32 offset:2304
	v_cndmask_b32_e64 v32, 0, 1, s[42:43]
	v_cndmask_b32_e64 v32, v33, v32, s[28:29]
	v_and_b32_e32 v32, 1, v32
	v_cmp_eq_u32_e32 vcc, 1, v32
	v_cndmask_b32_e64 v33, 0, 1, s[80:81]
	s_nop 0
	v_cndmask_b32_e32 v32, 0, v41, vcc
	v_cvt_pk_bf16_f32 v32, v32, v65
	ds_write_b16 v104, v32 offset:2448
	v_cndmask_b32_e64 v32, 0, 1, s[82:83]
	v_cndmask_b32_e64 v32, v33, v32, s[28:29]
	v_and_b32_e32 v32, 1, v32
	v_cmp_eq_u32_e32 vcc, 1, v32
	v_cndmask_b32_e64 v33, 0, 1, s[84:85]
	s_nop 0
	v_cndmask_b32_e32 v32, 0, v42, vcc
	v_cvt_pk_bf16_f32 v32, v32, v65
	ds_write_b16 v104, v32 offset:2592
	v_cndmask_b32_e64 v32, 0, 1, s[86:87]
	v_cndmask_b32_e64 v32, v33, v32, s[28:29]
	v_and_b32_e32 v32, 1, v32
	v_cmp_eq_u32_e32 vcc, 1, v32
	v_cndmask_b32_e64 v33, 0, 1, s[88:89]
	s_nop 0
	v_cndmask_b32_e32 v32, 0, v43, vcc
	v_cvt_pk_bf16_f32 v32, v32, v65
	ds_write_b16 v104, v32 offset:2736
	v_cndmask_b32_e64 v32, 0, 1, s[90:91]
	v_cndmask_b32_e64 v32, v33, v32, s[28:29]
	v_and_b32_e32 v32, 1, v32
	v_cmp_eq_u32_e32 vcc, 1, v32
	v_cndmask_b32_e64 v33, 0, 1, s[92:93]
	s_nop 0
	v_cndmask_b32_e32 v32, 0, v44, vcc
	v_cvt_pk_bf16_f32 v32, v32, v65
	ds_write_b16 v104, v32 offset:3456
	v_cndmask_b32_e64 v32, 0, 1, s[94:95]
	v_cndmask_b32_e64 v32, v33, v32, s[28:29]
	v_and_b32_e32 v32, 1, v32
	v_cmp_eq_u32_e32 vcc, 1, v32
	v_cndmask_b32_e64 v33, 0, 1, s[96:97]
	s_nop 0
	v_cndmask_b32_e32 v32, 0, v45, vcc
	v_cvt_pk_bf16_f32 v32, v32, v65
	ds_write_b16 v104, v32 offset:3600
	v_cndmask_b32_e64 v32, 0, 1, s[98:99]
	v_cndmask_b32_e64 v32, v33, v32, s[28:29]
	v_and_b32_e32 v32, 1, v32
	v_cmp_eq_u32_e32 vcc, 1, v32
	v_cndmask_b32_e64 v33, 0, 1, s[36:37]
	s_nop 0
	v_cndmask_b32_e32 v32, 0, v46, vcc
	v_cvt_pk_bf16_f32 v32, v32, v65
	ds_write_b16 v104, v32 offset:3744
	v_cndmask_b32_e64 v32, 0, 1, s[0:1]
	v_cndmask_b32_e64 v32, v33, v32, s[28:29]
	v_and_b32_e32 v32, 1, v32
	v_cmp_eq_u32_e32 vcc, 1, v32
	s_nop 1
	v_cndmask_b32_e32 v32, 0, v47, vcc
	v_cvt_pk_bf16_f32 v32, v32, v65
	ds_write_b16 v104, v32 offset:3888
	s_branch .LBB0_455
